# phase 1 deferred weight-conversion jobs: static assignment t = bid + 512k instead of an atomic queue pop (removes one device-scope atomic + two block barriers per job)
# speedup vs baseline: 1.0105x; 1.0105x over previous
.LBB0_452:
	s_mov_b32 s98, 0
	v_add_u32_e32 v5, 0x100, v200
	v_lshlrev_b32_e32 v0, 2, v200
	v_ashrrev_i32_e32 v3, 3, v200
	v_ashrrev_i32_e32 v5, 3, v5
	v_and_b32_e32 v22, 60, v0
	v_ashrrev_i32_e32 v23, 4, v200
	v_and_b32_e32 v25, 63, v200
	v_and_b32_e32 v16, -8, v3
	v_or_b32_e32 v3, 7, v3
	v_and_b32_e32 v18, -8, v5
	v_or_b32_e32 v5, 7, v5
	v_lshl_add_u32 v0, v22, 2, 0
	v_mul_lo_u32 v1, v23, s48
	v_lshl_add_u32 v2, v25, 2, 0
	v_mul_lo_u32 v4, v16, s48
	v_mul_lo_u32 v3, v3, s48
	v_mul_lo_u32 v6, v18, s48
	v_mul_lo_u32 v5, v5, s48
	v_cmp_eq_u32_e64 s[4:5], 0, v200
	v_cmp_gt_u32_e64 s[6:7], 32, v22
	v_add_u32_e32 v24, 0xae0, v22
	v_ashrrev_i32_e32 v17, 31, v16
	v_ashrrev_i32_e32 v19, 31, v18
	v_add_u32_e32 v26, v0, v1
	v_add_u32_e32 v27, v2, v4
	v_add_u32_e32 v28, v2, v3
	v_add_u32_e32 v29, v2, v6
	v_add_u32_e32 v30, v2, v5
	s_branch .LBB0_455

.LBB0_455:
	v_readlane_b32 s0, v251, 5
	s_lshr_b32 s0, s0, 2
	s_lshl_b32 s2, s98, 9
	s_add_i32 s2, s2, s0
	s_add_i32 s98, s98, 1
	v_mov_b32_e32 v0, s2
	s_movk_i32 s0, 0x580
	s_mov_b64 s[12:13], -1
	v_cmp_gt_i32_e32 vcc, s0, v0
	s_movk_i32 s0, 0x57f
	v_readfirstlane_b32 s2, v0
	v_cmp_lt_i32_e64 s[8:9], s0, v0
	s_cbranch_vccnz .LBB0_465
	s_add_i32 s1, s2, 0xfffffa80
	s_cmpk_lt_u32 s1, 0x2c0
	s_cbranch_scc1 .LBB0_466
	s_add_i32 s1, s2, 0xfffff7c0
	s_cmpk_lt_u32 s1, 0x100
	s_cbranch_scc1 .LBB0_467
	s_add_i32 s1, s2, 0xfffff6c0
	s_cmpk_lt_u32 s1, 0x80
	s_cbranch_scc1 .LBB0_468
	s_add_i32 s1, s2, 0xfffff640
	s_cmpk_lt_u32 s1, 0x80
	s_cbranch_scc1 .LBB0_469
	s_cmpk_lt_u32 s1, 0x180
	s_cselect_b64 s[16:17], -1, 0
	s_and_b64 s[10:11], s[16:17], exec
	s_movk_i32 s0, 0xfe80
	s_cselect_b32 s0, 0xffffff80, s0
	v_readlane_b32 s14, v251, 13
	v_readlane_b32 s18, v251, 40
	s_add_i32 s1, s0, s1
	s_movk_i32 s0, 0x400
	v_readlane_b32 s15, v251, 14
	v_readlane_b32 s19, v251, 41
	s_branch .LBB0_470
